# MLA tile bodies: exps of previous tile re-spaced evenly (3 per gap) between the QK MFMAs, dependence-preserving
# baseline (speedup 1.0000x reference)
.LBB0_1193:
	s_add_u32 s98, s32, 0x3600180
	s_addc_u32 s99, s85, 0
	s_add_i32 s17, s16, 0x12000
	s_add_i32 m0, s17, s66
	v_exp_f32_e32 v150, v64
	global_load_lds_dwordx4 v113, s[98:99]
	ds_read_b128 v[80:83], v199 offset:12288
	ds_read_b128 v[84:87], v199 offset:18432
	ds_read_b128 v[154:157], v200 offset:12288
	ds_read_b128 v[202:205], v200 offset:18432
	ds_read_b128 v[212:215], v199 offset:12352
	ds_read_b128 v[220:223], v199 offset:18496
	ds_read_b128 v[224:227], v200 offset:12352
	ds_read_b128 v[228:231], v200 offset:18496
	ds_read_b128 v[232:235], v199 offset:12416
	ds_read_b128 v[236:239], v199 offset:18560
	ds_read_b128 v[240:243], v200 offset:12416
	ds_read_b128 v[244:247], v200 offset:18560
	s_waitcnt lgkmcnt(0)
	v_mfma_f32_32x32x16_bf16 v[96:111], v[80:83], v[136:139], 0
	v_exp_f32_e32 v151, v65
	v_exp_f32_e32 v152, v48
	v_exp_f32_e32 v153, v49
	v_mfma_f32_32x32x16_bf16 v[80:95], v[84:87], v[136:139], 0
	v_exp_f32_e32 v167, v50
	v_exp_f32_e32 v169, v51
	v_exp_f32_e32 v201, v69
	v_mfma_f32_32x32x16_bf16 v[96:111], v[154:157], v[132:135], v[96:111]
	v_exp_f32_e32 v208, v52
	v_exp_f32_e32 v209, v55
	v_exp_f32_e32 v219, v74
	v_mfma_f32_32x32x16_bf16 v[96:111], v[212:215], v[128:131], v[96:111]
	v_exp_f32_e32 v155, v66
	v_exp_f32_e32 v156, v67
	v_exp_f32_e32 v157, v68
	v_mfma_f32_32x32x16_bf16 v[96:111], v[224:227], v[124:127], v[96:111]
	v_exp_f32_e32 v212, v72
	v_exp_f32_e32 v213, v73
	v_exp_f32_e32 v214, v56
	v_mfma_f32_32x32x16_bf16 v[96:111], v[232:235], v[120:123], v[96:111]
	v_exp_f32_e32 v215, v57
	v_exp_f32_e32 v224, v77
	v_exp_f32_e32 v225, v60
	v_mfma_f32_32x32x16_bf16 v[96:111], v[240:243], v[116:119], v[96:111]
	v_exp_f32_e32 v226, v61
	v_exp_f32_e32 v227, v78
	v_mfma_f32_32x32x16_bf16 v[80:95], v[202:205], v[132:135], v[80:95]
	v_exp_f32_e32 v202, v53
	v_exp_f32_e32 v203, v70
	v_exp_f32_e32 v204, v71
	v_mfma_f32_32x32x16_bf16 v[80:95], v[220:223], v[128:131], v[80:95]
	v_exp_f32_e32 v205, v54
	v_exp_f32_e32 v220, v75
	v_exp_f32_e32 v221, v58
	v_mfma_f32_32x32x16_bf16 v[80:95], v[228:231], v[124:127], v[80:95]
	v_exp_f32_e32 v222, v59
	v_exp_f32_e32 v223, v76
	v_exp_f32_e32 v228, v79
	v_exp_f32_e32 v229, v62
	v_exp_f32_e32 v230, v63
	v_mfma_f32_32x32x16_bf16 v[80:95], v[236:239], v[120:123], v[80:95]
	ds_read_b128 v[48:51], v173 offset:49152
	ds_read_b128 v[52:55], v173 offset:53248
	ds_read_b128 v[56:59], v197 offset:49152
	ds_read_b128 v[60:63], v197 offset:53248
	ds_read_b128 v[64:67], v193 offset:49152
	ds_read_b128 v[68:71], v193 offset:53248
	ds_read_b128 v[72:75], v195 offset:49152
	ds_read_b128 v[76:79], v195 offset:53248
	v_add_f32_e32 v32, v32, v150
	v_add_f32_e32 v33, v33, v151
	v_cvt_pk_bf16_f32 v154, v150, v151
	v_add_f32_e32 v34, v34, v155
	v_add_f32_e32 v35, v35, v156
	v_cvt_pk_bf16_f32 v155, v155, v156
	v_add_f32_e32 v32, v32, v157
	v_add_f32_e32 v33, v33, v201
	v_cvt_pk_bf16_f32 v156, v157, v201
	v_add_f32_e32 v34, v34, v203
	v_add_f32_e32 v35, v35, v204
	v_cvt_pk_bf16_f32 v157, v203, v204
	v_mfma_f32_32x32x16_bf16 v[80:95], v[244:247], v[116:119], v[80:95]
	s_and_b64 vcc, exec, s[6:7]
	s_waitcnt lgkmcnt(0)
	v_mfma_f32_32x32x16_bf16 v[16:31], v[52:55], v[154:157], v[16:31]
	v_mfma_f32_32x32x16_bf16 v[0:15], v[48:51], v[154:157], v[0:15]
	v_add_f32_e32 v32, v32, v212
	v_add_f32_e32 v33, v33, v213
	v_cvt_pk_bf16_f32 v48, v212, v213
	v_add_f32_e32 v34, v34, v219
	v_add_f32_e32 v35, v35, v220
	v_cvt_pk_bf16_f32 v49, v219, v220
	v_add_f32_e32 v32, v32, v223
	v_add_f32_e32 v33, v33, v224
	v_cvt_pk_bf16_f32 v50, v223, v224
	v_cvt_pk_bf16_f32 v51, v227, v228
	v_add_f32_e32 v34, v34, v227
	v_add_f32_e32 v35, v35, v228
	v_mfma_f32_32x32x16_bf16 v[16:31], v[60:63], v[48:51], v[16:31]
	v_mfma_f32_32x32x16_bf16 v[0:15], v[56:59], v[48:51], v[0:15]
	v_add_f32_e32 v32, v32, v152
	v_add_f32_e32 v33, v33, v153
	v_cvt_pk_bf16_f32 v52, v152, v153
	v_add_f32_e32 v34, v34, v167
	v_add_f32_e32 v35, v35, v169
	v_cvt_pk_bf16_f32 v53, v167, v169
	v_add_f32_e32 v32, v32, v208
	v_add_f32_e32 v33, v33, v202
	v_cvt_pk_bf16_f32 v54, v208, v202
	v_cvt_pk_bf16_f32 v55, v205, v209
	v_add_f32_e32 v34, v34, v205
	v_add_f32_e32 v35, v35, v209
	v_mfma_f32_32x32x16_bf16 v[16:31], v[68:71], v[52:55], v[16:31]
	v_mfma_f32_32x32x16_bf16 v[0:15], v[64:67], v[52:55], v[0:15]
	v_add_f32_e32 v32, v32, v214
	v_add_f32_e32 v33, v33, v215
	v_cvt_pk_bf16_f32 v48, v214, v215
	v_add_f32_e32 v34, v34, v221
	v_add_f32_e32 v35, v35, v222
	v_cvt_pk_bf16_f32 v49, v221, v222
	v_add_f32_e32 v32, v32, v225
	v_add_f32_e32 v33, v33, v226
	v_cvt_pk_bf16_f32 v50, v225, v226
	v_cvt_pk_bf16_f32 v51, v229, v230
	v_add_f32_e32 v34, v34, v229
	v_add_f32_e32 v35, v35, v230
	v_mfma_f32_32x32x16_bf16 v[16:31], v[76:79], v[48:51], v[16:31]
	v_mfma_f32_32x32x16_bf16 v[0:15], v[72:75], v[48:51], v[0:15]
	s_cbranch_vccz .Lmla_nf_0
.LBB0_1196:
	ds_read_b128 v[48:51], v199 offset:24576
	ds_read_b128 v[52:55], v199 offset:30720
	ds_read_b128 v[154:157], v200 offset:24576
	ds_read_b128 v[202:205], v200 offset:30720
	ds_read_b128 v[212:215], v199 offset:24640
	ds_read_b128 v[220:223], v199 offset:30784
	ds_read_b128 v[224:227], v200 offset:24640
	ds_read_b128 v[228:231], v200 offset:30784
	ds_read_b128 v[232:235], v199 offset:24704
	ds_read_b128 v[236:239], v199 offset:30848
	ds_read_b128 v[240:243], v200 offset:24704
	ds_read_b128 v[244:247], v200 offset:30848
	s_waitcnt lgkmcnt(0)
	v_mfma_f32_32x32x16_bf16 v[64:79], v[48:51], v[136:139], 0
	v_exp_f32_e32 v150, v96
	v_exp_f32_e32 v151, v97
	v_exp_f32_e32 v152, v80
	v_mfma_f32_32x32x16_bf16 v[48:63], v[52:55], v[136:139], 0
	v_exp_f32_e32 v153, v81
	v_exp_f32_e32 v167, v82
	v_exp_f32_e32 v169, v83
	v_mfma_f32_32x32x16_bf16 v[64:79], v[154:157], v[132:135], v[64:79]
	v_exp_f32_e32 v201, v101
	v_exp_f32_e32 v208, v84
	v_exp_f32_e32 v209, v87
	v_mfma_f32_32x32x16_bf16 v[64:79], v[212:215], v[128:131], v[64:79]
	v_exp_f32_e32 v219, v106
	v_exp_f32_e32 v155, v98
	v_exp_f32_e32 v156, v99
	v_mfma_f32_32x32x16_bf16 v[64:79], v[224:227], v[124:127], v[64:79]
	v_exp_f32_e32 v157, v100
	v_exp_f32_e32 v212, v104
	v_exp_f32_e32 v213, v105
	v_mfma_f32_32x32x16_bf16 v[64:79], v[232:235], v[120:123], v[64:79]
	v_exp_f32_e32 v214, v88
	v_exp_f32_e32 v215, v89
	v_exp_f32_e32 v224, v109
	v_mfma_f32_32x32x16_bf16 v[64:79], v[240:243], v[116:119], v[64:79]
	v_exp_f32_e32 v225, v92
	v_exp_f32_e32 v226, v93
	v_exp_f32_e32 v227, v110
	v_mfma_f32_32x32x16_bf16 v[48:63], v[202:205], v[132:135], v[48:63]
	v_exp_f32_e32 v202, v85
	v_exp_f32_e32 v203, v102
	v_exp_f32_e32 v204, v103
	v_mfma_f32_32x32x16_bf16 v[48:63], v[220:223], v[128:131], v[48:63]
	v_exp_f32_e32 v205, v86
	v_exp_f32_e32 v220, v107
	v_exp_f32_e32 v221, v90
	v_mfma_f32_32x32x16_bf16 v[48:63], v[228:231], v[124:127], v[48:63]
	v_exp_f32_e32 v222, v91
	v_exp_f32_e32 v223, v108
	v_exp_f32_e32 v228, v111
	v_exp_f32_e32 v229, v94
	v_exp_f32_e32 v230, v95
	v_mfma_f32_32x32x16_bf16 v[48:63], v[236:239], v[120:123], v[48:63]
	ds_read_b128 v[80:83], v173 offset:57344
	ds_read_b128 v[84:87], v173 offset:61440
	ds_read_b128 v[88:91], v197 offset:57344
	ds_read_b128 v[92:95], v197 offset:61440
	ds_read_b128 v[96:99], v193 offset:57344
	ds_read_b128 v[100:103], v193 offset:61440
	ds_read_b128 v[104:107], v195 offset:57344
	ds_read_b128 v[108:111], v195 offset:61440
	v_add_f32_e32 v32, v32, v150
	v_add_f32_e32 v33, v33, v151
	v_cvt_pk_bf16_f32 v154, v150, v151
	v_add_f32_e32 v34, v34, v155
	v_add_f32_e32 v35, v35, v156
	v_cvt_pk_bf16_f32 v155, v155, v156
	v_add_f32_e32 v32, v32, v157
	v_add_f32_e32 v33, v33, v201
	v_cvt_pk_bf16_f32 v156, v157, v201
	v_add_f32_e32 v34, v34, v203
	v_add_f32_e32 v35, v35, v204
	v_cvt_pk_bf16_f32 v157, v203, v204
	v_mfma_f32_32x32x16_bf16 v[48:63], v[244:247], v[116:119], v[48:63]
	s_cmp_eq_u32 s64, 0
	s_cbranch_scc1 .Lmla_late_skip0
	s_waitcnt vmcnt(0)
	s_barrier

.LBB0_1203:
	s_mov_b32 m0, s14
	s_add_u32 s98, s32, 0x3600280
	s_addc_u32 s99, s85, 0
	global_load_lds_dwordx4 v[82:83], off
	s_sub_i32 m0, s62, s66
	s_add_i32 m0, m0, 0x8000
	v_exp_f32_e32 v150, v64
	global_load_lds_dwordx4 v113, s[98:99]
	ds_read_b128 v[80:83], v199 offset:36864
	ds_read_b128 v[84:87], v199 offset:43008
	ds_read_b128 v[154:157], v200 offset:36864
	ds_read_b128 v[186:189], v200 offset:43008
	ds_read_b128 v[202:205], v199 offset:36928
	ds_read_b128 v[212:215], v199 offset:43072
	ds_read_b128 v[220:223], v200 offset:36928
	ds_read_b128 v[224:227], v200 offset:43072
	ds_read_b128 v[228:231], v199 offset:36992
	ds_read_b128 v[232:235], v199 offset:43136
	ds_read_b128 v[236:239], v200 offset:36992
	ds_read_b128 v[240:243], v200 offset:43136
	s_waitcnt lgkmcnt(0)
	v_mfma_f32_32x32x16_bf16 v[96:111], v[80:83], v[136:139], 0
	v_exp_f32_e32 v151, v65
	v_exp_f32_e32 v152, v48
	v_exp_f32_e32 v153, v49
	v_mfma_f32_32x32x16_bf16 v[80:95], v[84:87], v[136:139], 0
	v_exp_f32_e32 v167, v50
	v_exp_f32_e32 v169, v51
	v_exp_f32_e32 v190, v69
	v_mfma_f32_32x32x16_bf16 v[96:111], v[154:157], v[132:135], v[96:111]
	v_exp_f32_e32 v191, v52
	v_exp_f32_e32 v201, v55
	v_exp_f32_e32 v208, v74
	v_mfma_f32_32x32x16_bf16 v[96:111], v[202:205], v[128:131], v[96:111]
	v_exp_f32_e32 v209, v75
	v_exp_f32_e32 v219, v60
	v_exp_f32_e32 v155, v66
	v_mfma_f32_32x32x16_bf16 v[96:111], v[220:223], v[124:127], v[96:111]
	v_exp_f32_e32 v156, v67
	v_exp_f32_e32 v157, v68
	v_exp_f32_e32 v202, v72
	v_mfma_f32_32x32x16_bf16 v[96:111], v[228:231], v[120:123], v[96:111]
	v_exp_f32_e32 v203, v73
	v_exp_f32_e32 v204, v56
	v_exp_f32_e32 v205, v57
	v_mfma_f32_32x32x16_bf16 v[96:111], v[236:239], v[116:119], v[96:111]
	v_exp_f32_e32 v220, v61
	v_exp_f32_e32 v221, v78
	v_exp_f32_e32 v222, v79
	v_mfma_f32_32x32x16_bf16 v[80:95], v[186:189], v[132:135], v[80:95]
	v_exp_f32_e32 v223, v62
	v_exp_f32_e32 v186, v53
	v_exp_f32_e32 v187, v70
	v_mfma_f32_32x32x16_bf16 v[80:95], v[212:215], v[128:131], v[80:95]
	v_exp_f32_e32 v188, v71
	v_exp_f32_e32 v189, v54
	v_exp_f32_e32 v212, v58
	v_mfma_f32_32x32x16_bf16 v[80:95], v[224:227], v[124:127], v[80:95]
	v_exp_f32_e32 v213, v59
	v_exp_f32_e32 v214, v76
	v_exp_f32_e32 v215, v77
	v_exp_f32_e32 v224, v63
	v_mfma_f32_32x32x16_bf16 v[80:95], v[232:235], v[120:123], v[80:95]
	ds_read_b128 v[48:51], v192 offset:16384
	ds_read_b128 v[52:55], v192 offset:20480
	ds_read_b128 v[56:59], v198 offset:16384
	ds_read_b128 v[60:63], v198 offset:20480
	ds_read_b128 v[64:67], v194 offset:16384
	ds_read_b128 v[68:71], v194 offset:20480
	ds_read_b128 v[72:75], v196 offset:16384
	ds_read_b128 v[76:79], v196 offset:20480
	v_add_f32_e32 v32, v32, v150
	v_add_f32_e32 v33, v33, v151
	v_cvt_pk_bf16_f32 v154, v150, v151
	v_add_f32_e32 v34, v34, v155
	v_add_f32_e32 v35, v35, v156
	v_cvt_pk_bf16_f32 v155, v155, v156
	v_add_f32_e32 v32, v32, v157
	v_add_f32_e32 v33, v33, v190
	v_cvt_pk_bf16_f32 v156, v157, v190
	v_add_f32_e32 v34, v34, v187
	v_add_f32_e32 v35, v35, v188
	v_cvt_pk_bf16_f32 v157, v187, v188
	v_mfma_f32_32x32x16_bf16 v[80:95], v[240:243], v[116:119], v[80:95]
	s_and_b64 vcc, exec, s[6:7]
	s_waitcnt lgkmcnt(0)
	v_mfma_f32_32x32x16_bf16 v[16:31], v[52:55], v[154:157], v[16:31]
	v_mfma_f32_32x32x16_bf16 v[0:15], v[48:51], v[154:157], v[0:15]
	v_add_f32_e32 v32, v32, v202
	v_add_f32_e32 v33, v33, v203
	v_cvt_pk_bf16_f32 v48, v202, v203
	v_add_f32_e32 v34, v34, v208
	v_add_f32_e32 v35, v35, v209
	v_cvt_pk_bf16_f32 v49, v208, v209
	v_add_f32_e32 v32, v32, v214
	v_add_f32_e32 v33, v33, v215
	v_cvt_pk_bf16_f32 v50, v214, v215
	v_cvt_pk_bf16_f32 v51, v221, v222
	v_add_f32_e32 v34, v34, v221
	v_add_f32_e32 v35, v35, v222
	v_mfma_f32_32x32x16_bf16 v[16:31], v[60:63], v[48:51], v[16:31]
	v_mfma_f32_32x32x16_bf16 v[0:15], v[56:59], v[48:51], v[0:15]
	v_add_f32_e32 v32, v32, v152
	v_add_f32_e32 v33, v33, v153
	v_cvt_pk_bf16_f32 v52, v152, v153
	v_add_f32_e32 v34, v34, v167
	v_add_f32_e32 v35, v35, v169
	v_cvt_pk_bf16_f32 v53, v167, v169
	v_add_f32_e32 v32, v32, v191
	v_add_f32_e32 v33, v33, v186
	v_cvt_pk_bf16_f32 v54, v191, v186
	v_cvt_pk_bf16_f32 v55, v189, v201
	v_add_f32_e32 v34, v34, v189
	v_add_f32_e32 v35, v35, v201
	v_mfma_f32_32x32x16_bf16 v[16:31], v[68:71], v[52:55], v[16:31]
	v_mfma_f32_32x32x16_bf16 v[0:15], v[64:67], v[52:55], v[0:15]
	v_add_f32_e32 v32, v32, v204
	v_add_f32_e32 v33, v33, v205
	v_cvt_pk_bf16_f32 v48, v204, v205
	v_add_f32_e32 v34, v34, v212
	v_add_f32_e32 v35, v35, v213
	v_cvt_pk_bf16_f32 v49, v212, v213
	v_add_f32_e32 v32, v32, v219
	v_add_f32_e32 v33, v33, v220
	v_cvt_pk_bf16_f32 v50, v219, v220
	v_cvt_pk_bf16_f32 v51, v223, v224
	v_add_f32_e32 v34, v34, v223
	v_add_f32_e32 v35, v35, v224
	v_mfma_f32_32x32x16_bf16 v[16:31], v[76:79], v[48:51], v[16:31]
	v_mfma_f32_32x32x16_bf16 v[0:15], v[72:75], v[48:51], v[0:15]
	s_cbranch_vccz .Lmla_nf_2
.LBB0_1206:
	ds_read_b128 v[48:51], v199
	ds_read_b128 v[52:55], v199 offset:6144
	ds_read_b128 v[154:157], v200
	ds_read_b128 v[186:189], v200 offset:6144
	ds_read_b128 v[202:205], v199 offset:64
	ds_read_b128 v[212:215], v199 offset:6208
	ds_read_b128 v[220:223], v200 offset:64
	ds_read_b128 v[224:227], v200 offset:6208
	ds_read_b128 v[228:231], v199 offset:128
	ds_read_b128 v[232:235], v199 offset:6272
	ds_read_b128 v[236:239], v200 offset:128
	ds_read_b128 v[240:243], v200 offset:6272
	s_waitcnt lgkmcnt(0)
	v_mfma_f32_32x32x16_bf16 v[64:79], v[48:51], v[136:139], 0
	v_exp_f32_e32 v150, v96
	v_exp_f32_e32 v151, v97
	v_exp_f32_e32 v152, v80
	v_mfma_f32_32x32x16_bf16 v[48:63], v[52:55], v[136:139], 0
	v_exp_f32_e32 v153, v81
	v_exp_f32_e32 v167, v82
	v_exp_f32_e32 v169, v83
	v_mfma_f32_32x32x16_bf16 v[64:79], v[154:157], v[132:135], v[64:79]
	v_exp_f32_e32 v190, v101
	v_exp_f32_e32 v191, v84
	v_exp_f32_e32 v201, v87
	v_mfma_f32_32x32x16_bf16 v[64:79], v[202:205], v[128:131], v[64:79]
	v_exp_f32_e32 v208, v106
	v_exp_f32_e32 v209, v107
	v_exp_f32_e32 v219, v92
	v_mfma_f32_32x32x16_bf16 v[64:79], v[220:223], v[124:127], v[64:79]
	v_exp_f32_e32 v155, v98
	v_exp_f32_e32 v156, v99
	v_exp_f32_e32 v157, v100
	v_mfma_f32_32x32x16_bf16 v[64:79], v[228:231], v[120:123], v[64:79]
	v_exp_f32_e32 v202, v104
	v_exp_f32_e32 v203, v105
	v_exp_f32_e32 v204, v88
	v_mfma_f32_32x32x16_bf16 v[64:79], v[236:239], v[116:119], v[64:79]
	v_exp_f32_e32 v205, v89
	v_exp_f32_e32 v220, v93
	v_exp_f32_e32 v221, v110
	v_mfma_f32_32x32x16_bf16 v[48:63], v[186:189], v[132:135], v[48:63]
	v_exp_f32_e32 v222, v111
	v_exp_f32_e32 v223, v94
	v_exp_f32_e32 v186, v85
	v_mfma_f32_32x32x16_bf16 v[48:63], v[212:215], v[128:131], v[48:63]
	v_exp_f32_e32 v187, v102
	v_exp_f32_e32 v188, v103
	v_exp_f32_e32 v189, v86
	v_mfma_f32_32x32x16_bf16 v[48:63], v[224:227], v[124:127], v[48:63]
	v_exp_f32_e32 v212, v90
	v_exp_f32_e32 v213, v91
	v_exp_f32_e32 v214, v108
	v_exp_f32_e32 v215, v109
	v_exp_f32_e32 v224, v95
	v_mfma_f32_32x32x16_bf16 v[48:63], v[232:235], v[120:123], v[48:63]
	ds_read_b128 v[80:83], v192 offset:24576
	ds_read_b128 v[84:87], v192 offset:28672
	ds_read_b128 v[88:91], v198 offset:24576
	ds_read_b128 v[92:95], v198 offset:28672
	ds_read_b128 v[96:99], v194 offset:24576
	ds_read_b128 v[100:103], v194 offset:28672
	ds_read_b128 v[104:107], v196 offset:24576
	ds_read_b128 v[108:111], v196 offset:28672
	v_add_f32_e32 v32, v32, v150
	v_add_f32_e32 v33, v33, v151
	v_cvt_pk_bf16_f32 v154, v150, v151
	v_add_f32_e32 v34, v34, v155
	v_add_f32_e32 v35, v35, v156
	v_cvt_pk_bf16_f32 v155, v155, v156
	v_add_f32_e32 v32, v32, v157
	v_add_f32_e32 v33, v33, v190
	v_cvt_pk_bf16_f32 v156, v157, v190
	v_add_f32_e32 v34, v34, v187
	v_add_f32_e32 v35, v35, v188
	v_cvt_pk_bf16_f32 v157, v187, v188
	v_mfma_f32_32x32x16_bf16 v[48:63], v[240:243], v[116:119], v[48:63]
	s_cmp_eq_u32 s64, 0
	s_cbranch_scc1 .Lmla_late_skip1
	s_waitcnt vmcnt(0)
	s_barrier

.LBB0_1213:
	s_mov_b32 m0, s12
	v_lshl_add_u64 v[80:81], v[84:85], 0, s[8:9]
	s_mov_b64 s[8:9], 0x1f80
	global_load_lds_dwordx4 v[80:81], off
	v_lshl_add_u64 v[80:81], v[178:179], 0, s[8:9]
	s_add_i32 m0, s17, s66
	v_exp_f32_e32 v150, v64
	global_load_lds_dwordx4 v[80:81], off
	ds_read_b128 v[80:83], v199 offset:12288
	ds_read_b128 v[84:87], v199 offset:18432
	ds_read_b128 v[154:157], v200 offset:12288
	ds_read_b128 v[176:179], v200 offset:18432
	ds_read_b128 v[180:183], v199 offset:12352
	ds_read_b128 v[184:187], v199 offset:18496
	ds_read_b128 v[188:191], v200 offset:12352
	ds_read_b128 v[202:205], v200 offset:18496
	ds_read_b128 v[212:215], v199 offset:12416
	ds_read_b128 v[220:223], v199 offset:18560
	ds_read_b128 v[224:227], v200 offset:12416
	ds_read_b128 v[228:231], v200 offset:18560
	s_waitcnt lgkmcnt(0)
	v_mfma_f32_32x32x16_bf16 v[96:111], v[80:83], v[136:139], 0
	v_exp_f32_e32 v151, v65
	v_exp_f32_e32 v152, v48
	v_exp_f32_e32 v153, v49
	v_mfma_f32_32x32x16_bf16 v[80:95], v[84:87], v[136:139], 0
	v_exp_f32_e32 v167, v50
	v_exp_f32_e32 v169, v51
	v_exp_f32_e32 v201, v77
	v_mfma_f32_32x32x16_bf16 v[96:111], v[154:157], v[132:135], v[96:111]
	v_exp_f32_e32 v208, v62
	v_exp_f32_e32 v209, v63
	v_exp_f32_e32 v155, v66
	v_mfma_f32_32x32x16_bf16 v[96:111], v[180:183], v[128:131], v[96:111]
	v_exp_f32_e32 v156, v67
	v_exp_f32_e32 v157, v68
	v_exp_f32_e32 v180, v69
	v_mfma_f32_32x32x16_bf16 v[96:111], v[188:191], v[124:127], v[96:111]
	v_exp_f32_e32 v181, v52
	v_exp_f32_e32 v182, v55
	v_exp_f32_e32 v183, v72
	v_mfma_f32_32x32x16_bf16 v[96:111], v[212:215], v[120:123], v[96:111]
	v_exp_f32_e32 v188, v73
	v_exp_f32_e32 v189, v58
	v_exp_f32_e32 v190, v59
	v_mfma_f32_32x32x16_bf16 v[96:111], v[224:227], v[116:119], v[96:111]
	v_exp_f32_e32 v191, v76
	v_mfma_f32_32x32x16_bf16 v[80:95], v[176:179], v[132:135], v[80:95]
	v_exp_f32_e32 v176, v53
	v_exp_f32_e32 v177, v70
	v_exp_f32_e32 v178, v71
	v_mfma_f32_32x32x16_bf16 v[80:95], v[184:187], v[128:131], v[80:95]
	v_exp_f32_e32 v179, v54
	v_exp_f32_e32 v184, v56
	v_exp_f32_e32 v185, v57
	v_mfma_f32_32x32x16_bf16 v[80:95], v[202:205], v[124:127], v[80:95]
	v_exp_f32_e32 v186, v74
	v_exp_f32_e32 v187, v75
	v_exp_f32_e32 v202, v60
	v_exp_f32_e32 v203, v61
	v_exp_f32_e32 v204, v78
	v_exp_f32_e32 v205, v79
	v_mfma_f32_32x32x16_bf16 v[80:95], v[220:223], v[120:123], v[80:95]
	ds_read_b128 v[48:51], v173 offset:49152
	ds_read_b128 v[52:55], v173 offset:53248
	ds_read_b128 v[56:59], v197 offset:49152
	ds_read_b128 v[60:63], v197 offset:53248
	ds_read_b128 v[64:67], v193 offset:49152
	ds_read_b128 v[68:71], v193 offset:53248
	ds_read_b128 v[72:75], v195 offset:49152
	ds_read_b128 v[76:79], v195 offset:53248
	v_add_f32_e32 v32, v32, v150
	v_add_f32_e32 v33, v33, v151
	v_cvt_pk_bf16_f32 v154, v150, v151
	v_add_f32_e32 v34, v34, v155
	v_add_f32_e32 v35, v35, v156
	v_cvt_pk_bf16_f32 v155, v155, v156
	v_add_f32_e32 v32, v32, v157
	v_add_f32_e32 v33, v33, v180
	v_cvt_pk_bf16_f32 v156, v157, v180
	v_add_f32_e32 v34, v34, v177
	v_add_f32_e32 v35, v35, v178
	v_cvt_pk_bf16_f32 v157, v177, v178
	v_mfma_f32_32x32x16_bf16 v[80:95], v[228:231], v[116:119], v[80:95]
	s_and_b64 vcc, exec, s[6:7]
	s_waitcnt lgkmcnt(0)
	v_mfma_f32_32x32x16_bf16 v[16:31], v[52:55], v[154:157], v[16:31]
	v_mfma_f32_32x32x16_bf16 v[0:15], v[48:51], v[154:157], v[0:15]
	v_add_f32_e32 v32, v32, v183
	v_add_f32_e32 v33, v33, v188
	v_cvt_pk_bf16_f32 v48, v183, v188
	v_add_f32_e32 v34, v34, v186
	v_add_f32_e32 v35, v35, v187
	v_cvt_pk_bf16_f32 v49, v186, v187
	v_add_f32_e32 v32, v32, v191
	v_add_f32_e32 v33, v33, v201
	v_cvt_pk_bf16_f32 v50, v191, v201
	v_cvt_pk_bf16_f32 v51, v204, v205
	v_add_f32_e32 v34, v34, v204
	v_add_f32_e32 v35, v35, v205
	v_mfma_f32_32x32x16_bf16 v[16:31], v[60:63], v[48:51], v[16:31]
	v_mfma_f32_32x32x16_bf16 v[0:15], v[56:59], v[48:51], v[0:15]
	v_add_f32_e32 v32, v32, v152
	v_add_f32_e32 v33, v33, v153
	v_cvt_pk_bf16_f32 v52, v152, v153
	v_add_f32_e32 v34, v34, v167
	v_add_f32_e32 v35, v35, v169
	v_cvt_pk_bf16_f32 v53, v167, v169
	v_add_f32_e32 v32, v32, v181
	v_add_f32_e32 v33, v33, v176
	v_cvt_pk_bf16_f32 v54, v181, v176
	v_cvt_pk_bf16_f32 v55, v179, v182
	v_add_f32_e32 v34, v34, v179
	v_add_f32_e32 v35, v35, v182
	v_mfma_f32_32x32x16_bf16 v[16:31], v[68:71], v[52:55], v[16:31]
	v_mfma_f32_32x32x16_bf16 v[0:15], v[64:67], v[52:55], v[0:15]
	v_add_f32_e32 v32, v32, v184
	v_add_f32_e32 v33, v33, v185
	v_cvt_pk_bf16_f32 v48, v184, v185
	v_add_f32_e32 v34, v34, v189
	v_add_f32_e32 v35, v35, v190
	v_cvt_pk_bf16_f32 v49, v189, v190
	v_add_f32_e32 v32, v32, v202
	v_add_f32_e32 v33, v33, v203
	v_cvt_pk_bf16_f32 v50, v202, v203
	v_cvt_pk_bf16_f32 v51, v208, v209
	v_add_f32_e32 v34, v34, v208
	v_add_f32_e32 v35, v35, v209
	v_mfma_f32_32x32x16_bf16 v[16:31], v[76:79], v[48:51], v[16:31]
	v_mfma_f32_32x32x16_bf16 v[0:15], v[72:75], v[48:51], v[0:15]
	s_cbranch_vccz .Lmla_nf_3
.LBB0_1216:
	ds_read_b128 v[48:51], v199 offset:24576
	ds_read_b128 v[52:55], v199 offset:30720
	ds_read_b128 v[154:157], v200 offset:24576
	ds_read_b128 v[176:179], v200 offset:30720
	ds_read_b128 v[180:183], v199 offset:24640
	ds_read_b128 v[184:187], v199 offset:30784
	ds_read_b128 v[188:191], v200 offset:24640
	ds_read_b128 v[202:205], v200 offset:30784
	ds_read_b128 v[212:215], v199 offset:24704
	ds_read_b128 v[220:223], v199 offset:30848
	ds_read_b128 v[224:227], v200 offset:24704
	ds_read_b128 v[228:231], v200 offset:30848
	s_waitcnt lgkmcnt(0)
	v_mfma_f32_32x32x16_bf16 v[64:79], v[48:51], v[136:139], 0
	v_exp_f32_e32 v150, v96
	v_exp_f32_e32 v151, v97
	v_exp_f32_e32 v152, v80
	v_mfma_f32_32x32x16_bf16 v[48:63], v[52:55], v[136:139], 0
	v_exp_f32_e32 v153, v81
	v_exp_f32_e32 v167, v82
	v_exp_f32_e32 v169, v83
	v_mfma_f32_32x32x16_bf16 v[64:79], v[154:157], v[132:135], v[64:79]
	v_exp_f32_e32 v201, v109
	v_exp_f32_e32 v208, v94
	v_exp_f32_e32 v209, v95
	v_mfma_f32_32x32x16_bf16 v[64:79], v[180:183], v[128:131], v[64:79]
	v_exp_f32_e32 v155, v98
	v_exp_f32_e32 v156, v99
	v_exp_f32_e32 v157, v100
	v_mfma_f32_32x32x16_bf16 v[64:79], v[188:191], v[124:127], v[64:79]
	v_exp_f32_e32 v180, v101
	v_exp_f32_e32 v181, v84
	v_exp_f32_e32 v182, v87
	v_mfma_f32_32x32x16_bf16 v[64:79], v[212:215], v[120:123], v[64:79]
	v_exp_f32_e32 v183, v104
	v_exp_f32_e32 v188, v105
	v_exp_f32_e32 v189, v90
	v_mfma_f32_32x32x16_bf16 v[64:79], v[224:227], v[116:119], v[64:79]
	v_exp_f32_e32 v190, v91
	v_exp_f32_e32 v191, v108
	v_mfma_f32_32x32x16_bf16 v[48:63], v[176:179], v[132:135], v[48:63]
	v_exp_f32_e32 v176, v85
	v_exp_f32_e32 v177, v102
	v_exp_f32_e32 v178, v103
	v_mfma_f32_32x32x16_bf16 v[48:63], v[184:187], v[128:131], v[48:63]
	v_exp_f32_e32 v179, v86
	v_exp_f32_e32 v184, v88
	v_exp_f32_e32 v185, v89
	v_mfma_f32_32x32x16_bf16 v[48:63], v[202:205], v[124:127], v[48:63]
	v_exp_f32_e32 v186, v106
	v_exp_f32_e32 v187, v107
	v_exp_f32_e32 v202, v92
	v_exp_f32_e32 v203, v93
	v_exp_f32_e32 v204, v110
	v_exp_f32_e32 v205, v111
	v_mfma_f32_32x32x16_bf16 v[48:63], v[220:223], v[120:123], v[48:63]
	ds_read_b128 v[80:83], v173 offset:57344
	ds_read_b128 v[84:87], v173 offset:61440
	ds_read_b128 v[88:91], v197 offset:57344
	ds_read_b128 v[92:95], v197 offset:61440
	ds_read_b128 v[96:99], v193 offset:57344
	ds_read_b128 v[100:103], v193 offset:61440
	ds_read_b128 v[104:107], v195 offset:57344
	ds_read_b128 v[108:111], v195 offset:61440
	v_add_f32_e32 v32, v32, v150
	v_add_f32_e32 v33, v33, v151
	v_cvt_pk_bf16_f32 v154, v150, v151
	v_add_f32_e32 v34, v34, v155
	v_add_f32_e32 v35, v35, v156
	v_cvt_pk_bf16_f32 v155, v155, v156
	v_add_f32_e32 v32, v32, v157
	v_add_f32_e32 v33, v33, v180
	v_cvt_pk_bf16_f32 v156, v157, v180
	v_add_f32_e32 v34, v34, v177
	v_add_f32_e32 v35, v35, v178
	v_cvt_pk_bf16_f32 v157, v177, v178
	v_mfma_f32_32x32x16_bf16 v[48:63], v[228:231], v[116:119], v[48:63]
	s_cmp_eq_u32 s64, 0
	s_cbranch_scc1 .Lmla_late_skip2
	s_waitcnt vmcnt(0)
	s_barrier

.Lmla_early_skip2:
	s_sub_i32 m0, s60, s66
	s_add_i32 m0, m0, 0x8000
	v_exp_f32_e32 v150, v64
	global_load_lds_dwordx4 v[80:81], off
	ds_read_b128 v[80:83], v199 offset:36864
	ds_read_b128 v[84:87], v199 offset:43008
	ds_read_b128 v[154:157], v200 offset:36864
	ds_read_b128 v[174:177], v200 offset:43008
	ds_read_b128 v[178:181], v199 offset:36928
	ds_read_b128 v[182:185], v199 offset:43072
	ds_read_b128 v[186:189], v200 offset:36928
	ds_read_b128 v[202:205], v200 offset:43072
	ds_read_b128 v[212:215], v199 offset:36992
	ds_read_b128 v[220:223], v199 offset:43136
	ds_read_b128 v[224:227], v200 offset:36992
	ds_read_b128 v[228:231], v200 offset:43136
	s_waitcnt lgkmcnt(0)
	v_mfma_f32_32x32x16_bf16 v[96:111], v[80:83], v[136:139], 0
	v_exp_f32_e32 v151, v65
	v_exp_f32_e32 v152, v48
	v_exp_f32_e32 v153, v49
	v_mfma_f32_32x32x16_bf16 v[80:95], v[84:87], v[136:139], 0
	v_exp_f32_e32 v167, v50
	v_exp_f32_e32 v169, v51
	v_exp_f32_e32 v190, v77
	v_mfma_f32_32x32x16_bf16 v[96:111], v[154:157], v[132:135], v[96:111]
	v_exp_f32_e32 v191, v60
	v_exp_f32_e32 v201, v61
	v_exp_f32_e32 v155, v66
	v_mfma_f32_32x32x16_bf16 v[96:111], v[178:181], v[128:131], v[96:111]
	v_exp_f32_e32 v156, v67
	v_exp_f32_e32 v157, v68
	v_exp_f32_e32 v178, v69
	v_mfma_f32_32x32x16_bf16 v[96:111], v[186:189], v[124:127], v[96:111]
	v_exp_f32_e32 v179, v52
	v_exp_f32_e32 v180, v55
	v_exp_f32_e32 v181, v72
	v_mfma_f32_32x32x16_bf16 v[96:111], v[212:215], v[120:123], v[96:111]
	v_exp_f32_e32 v186, v73
	v_exp_f32_e32 v187, v58
	v_exp_f32_e32 v188, v59
	v_mfma_f32_32x32x16_bf16 v[96:111], v[224:227], v[116:119], v[96:111]
	v_exp_f32_e32 v189, v76
	v_mfma_f32_32x32x16_bf16 v[80:95], v[174:177], v[132:135], v[80:95]
	v_exp_f32_e32 v174, v53
	v_exp_f32_e32 v175, v70
	v_exp_f32_e32 v176, v71
	v_mfma_f32_32x32x16_bf16 v[80:95], v[182:185], v[128:131], v[80:95]
	v_exp_f32_e32 v177, v54
	v_exp_f32_e32 v182, v56
	v_exp_f32_e32 v183, v57
	v_mfma_f32_32x32x16_bf16 v[80:95], v[202:205], v[124:127], v[80:95]
	v_exp_f32_e32 v184, v74
	v_exp_f32_e32 v185, v75
	v_exp_f32_e32 v202, v78
	v_exp_f32_e32 v203, v79
	v_exp_f32_e32 v204, v62
	v_exp_f32_e32 v205, v63
	v_mfma_f32_32x32x16_bf16 v[80:95], v[220:223], v[120:123], v[80:95]
	ds_read_b128 v[48:51], v192 offset:16384
	ds_read_b128 v[52:55], v192 offset:20480
	ds_read_b128 v[56:59], v198 offset:16384
	ds_read_b128 v[60:63], v198 offset:20480
	ds_read_b128 v[64:67], v194 offset:16384
	ds_read_b128 v[68:71], v194 offset:20480
	ds_read_b128 v[72:75], v196 offset:16384
	ds_read_b128 v[76:79], v196 offset:20480
	v_add_f32_e32 v32, v32, v150
	v_add_f32_e32 v33, v33, v151
	v_cvt_pk_bf16_f32 v154, v150, v151
	v_add_f32_e32 v34, v34, v155
	v_add_f32_e32 v35, v35, v156
	v_cvt_pk_bf16_f32 v155, v155, v156
	v_add_f32_e32 v32, v32, v157
	v_add_f32_e32 v33, v33, v178
	v_cvt_pk_bf16_f32 v156, v157, v178
	v_add_f32_e32 v34, v34, v175
	v_add_f32_e32 v35, v35, v176
	v_cvt_pk_bf16_f32 v157, v175, v176
	v_mfma_f32_32x32x16_bf16 v[80:95], v[228:231], v[116:119], v[80:95]
	s_and_b64 vcc, exec, s[6:7]
	s_waitcnt lgkmcnt(0)
	v_mfma_f32_32x32x16_bf16 v[16:31], v[52:55], v[154:157], v[16:31]
	v_mfma_f32_32x32x16_bf16 v[0:15], v[48:51], v[154:157], v[0:15]
	v_add_f32_e32 v32, v32, v181
	v_add_f32_e32 v33, v33, v186
	v_cvt_pk_bf16_f32 v48, v181, v186
	v_add_f32_e32 v34, v34, v184
	v_add_f32_e32 v35, v35, v185
	v_cvt_pk_bf16_f32 v49, v184, v185
	v_add_f32_e32 v32, v32, v189
	v_add_f32_e32 v33, v33, v190
	v_cvt_pk_bf16_f32 v50, v189, v190
	v_cvt_pk_bf16_f32 v51, v202, v203
	v_add_f32_e32 v34, v34, v202
	v_add_f32_e32 v35, v35, v203
	v_mfma_f32_32x32x16_bf16 v[16:31], v[60:63], v[48:51], v[16:31]
	v_mfma_f32_32x32x16_bf16 v[0:15], v[56:59], v[48:51], v[0:15]
	v_add_f32_e32 v32, v32, v152
	v_add_f32_e32 v33, v33, v153
	v_cvt_pk_bf16_f32 v52, v152, v153
	v_add_f32_e32 v34, v34, v167
	v_add_f32_e32 v35, v35, v169
	v_cvt_pk_bf16_f32 v53, v167, v169
	v_add_f32_e32 v32, v32, v179
	v_add_f32_e32 v33, v33, v174
	v_cvt_pk_bf16_f32 v54, v179, v174
	v_cvt_pk_bf16_f32 v55, v177, v180
	v_add_f32_e32 v34, v34, v177
	v_add_f32_e32 v35, v35, v180
	v_mfma_f32_32x32x16_bf16 v[16:31], v[68:71], v[52:55], v[16:31]
	v_mfma_f32_32x32x16_bf16 v[0:15], v[64:67], v[52:55], v[0:15]
	v_add_f32_e32 v32, v32, v182
	v_add_f32_e32 v33, v33, v183
	v_cvt_pk_bf16_f32 v48, v182, v183
	v_add_f32_e32 v34, v34, v187
	v_add_f32_e32 v35, v35, v188
	v_cvt_pk_bf16_f32 v49, v187, v188
	v_add_f32_e32 v32, v32, v191
	v_add_f32_e32 v33, v33, v201
	v_cvt_pk_bf16_f32 v50, v191, v201
	v_cvt_pk_bf16_f32 v51, v204, v205
	v_add_f32_e32 v34, v34, v204
	v_add_f32_e32 v35, v35, v205
	v_mfma_f32_32x32x16_bf16 v[16:31], v[76:79], v[48:51], v[16:31]
	v_mfma_f32_32x32x16_bf16 v[0:15], v[72:75], v[48:51], v[0:15]
	s_cbranch_vccz .Lmla_nf_5
